# GEMM K-loop: LDS reads issued first in every load segment; loop-counter adds moved into the last (light) load segment
# baseline (speedup 1.0000x reference)
; #define PG8_STAGE(bufoff, gbase, voff) do { _Pragma("unroll") for (int _i = 0; _i < 2; ++_i) \
;         __builtin_amdgcn_global_load_lds((const unsigned*)((const char*)(gbase) + (voff)[_i]), (LAS unsigned*)(lds + (bufoff) + ldsw + _i * 8192), 16, 0, 0); } while (0)
; #define PG8_LDA(dst, b, h) do { _Pragma("unroll") for (int m = 0; m < 4; ++m) _Pragma("unroll") for (int k = 0; k < 2; ++k) dst[m][k] = *(const LAS f16x8*)(lds + PG8_SA(b, h) + aoff + m * 2048 + k * 1024); } while (0)
; #define PG8_LDB(dst, b, h) do { _Pragma("unroll") for (int n = 0; n < 2; ++n) _Pragma("unroll") for (int k = 0; k < 2; ++k) dst[n][k] = *(const LAS f16x8*)(lds + PG8_SB(b, h) + boff + n * 2048 + k * 1024); } while (0)
; #define PG8_MMA(ai, bj, At, Bt) do { __builtin_amdgcn_s_setprio(1); _Pragma("unroll") for (int m = 0; m < 4; ++m) _Pragma("unroll") for (int n = 0; n < 2; ++n) _Pragma("unroll") for (int k = 0; k < 2; ++k) \
;         acc[ai][bj][m][n] = __builtin_amdgcn_mfma_f32_16x16x32_f16(Bt[n][k], At[m][k], acc[ai][bj][m][n], 0, 0, 0); __builtin_amdgcn_s_setprio(0); } while (0)
; #define PG8_WAIT_L(n) asm volatile("s_waitcnt lgkmcnt(" #n ")" ::: "memory")
; #define PG8_BAR __builtin_amdgcn_s_barrier()
; #define PG8_SCHED __builtin_amdgcn_sched_barrier(0)
; template <class Epi, class Sched>
; __device__ __forceinline__ void gemm_phase(LAS unsigned char* lds, const Gemm g, const Sched& S, const Epi& E) {
;     ...
;         for (int t = 0; t < nt; t += 2) {
;             const bool last = (t == nt - 2);
;             const char* a1 = cA + (size_t)(t + 1) * kstep;
;             const char* a2 = last ? nA : cA + (size_t)(t + 2) * kstep; const char* b2 = last ? nB : cB + (size_t)(t + 2) * kstep;
;             const char* a3 = a2 + kstep; const char* b3 = b2 + kstep;
;             if (last && has_next) S.a_ready(nxt);
;             PG8_LDB(B0, 0, 0); PG8_SCHED; PG8_LDA(At, 0, 0); PG8_STAGE(PG8_SA(1, 1), a1 + hstep, voffA);
;             PG8_WAIT_L(8); PG8_BAR; PG8_WAIT_L(0); PG8_MMA(0, 0, At, B0); PG8_BAR; PG8_SCHED;
;             PG8_LDB(B1, 0, 1); PG8_STAGE(PG8_SB(0, 0), b2, voffB);
;             PG8_BAR; PG8_WAIT_L(0); PG8_MMA(0, 1, At, B1); PG8_BAR;
;             PG8_LDA(At, 0, 1); PG8_STAGE(PG8_SA(0, 0), a2, voffA);
;             PG8_BAR; PG8_WAIT_L(0); PG8_MMA(1, 0, At, B0); PG8_BAR; PG8_SCHED;
.LBB0_829:
	ds_read_b128 v[166:169], v161
	ds_read_b128 v[170:173], v161 offset:1024
	ds_read_b128 v[174:177], v161 offset:2048
	ds_read_b128 v[178:181], v161 offset:3072
	ds_read_b128 v[182:185], v161 offset:4096
	ds_read_b128 v[186:189], v161 offset:5120
	ds_read_b128 v[190:193], v161 offset:6144
	ds_read_b128 v[194:197], v161 offset:7168
	s_add_i32 vcc_hi, s8, 2
	s_add_u32 s10, s6, 0x80
	s_addc_u32 s9, s7, 0
	s_add_i32 s17, 0, 0x10000
	s_cmp_eq_u32 s40, s8
	s_cselect_b32 s8, s66, s10
	s_cselect_b32 s9, s67, s9
	s_cselect_b32 s11, s69, vcc_lo
	s_cselect_b32 s10, s68, s41
	v_lshl_add_u64 v[156:157], s[6:7], 0, v[140:141]
	s_add_i32 m0, s82, 0xc000
	global_load_lds_dwordx4 v[156:157], off
	v_lshl_add_u64 v[156:157], s[6:7], 0, v[142:143]
	s_add_i32 m0, s82, 0xe000
	s_nop 0
	global_load_lds_dwordx4 v[156:157], off
	s_waitcnt lgkmcnt(8)
	s_barrier
	s_waitcnt lgkmcnt(0)
	s_setprio 1
	s_waitcnt lgkmcnt(0)
	v_mfma_f32_16x16x32_f16 v[126:129], v[144:147], v[166:169], v[126:129]
	v_mfma_f32_16x16x32_f16 v[122:125], v[152:155], v[166:169], v[122:125]
	v_mfma_f32_16x16x32_f16 v[110:113], v[144:147], v[174:177], v[110:113]
	v_mfma_f32_16x16x32_f16 v[106:109], v[152:155], v[174:177], v[106:109]
	v_mfma_f32_16x16x32_f16 v[94:97], v[144:147], v[182:185], v[94:97]
	v_mfma_f32_16x16x32_f16 v[90:93], v[152:155], v[182:185], v[90:93]
	v_mfma_f32_16x16x32_f16 v[78:81], v[144:147], v[190:193], v[78:81]
	v_mfma_f32_16x16x32_f16 v[74:77], v[152:155], v[190:193], v[74:77]
	v_mfma_f32_16x16x32_f16 v[126:129], v[148:151], v[170:173], v[126:129]
	v_mfma_f32_16x16x32_f16 v[122:125], v[162:165], v[170:173], v[122:125]
	v_mfma_f32_16x16x32_f16 v[110:113], v[148:151], v[178:181], v[110:113]
	v_mfma_f32_16x16x32_f16 v[106:109], v[162:165], v[178:181], v[106:109]
	v_mfma_f32_16x16x32_f16 v[94:97], v[148:151], v[186:189], v[94:97]
	v_mfma_f32_16x16x32_f16 v[90:93], v[162:165], v[186:189], v[90:93]
	v_mfma_f32_16x16x32_f16 v[78:81], v[148:151], v[194:197], v[78:81]
	v_mfma_f32_16x16x32_f16 v[74:77], v[162:165], v[194:197], v[74:77]
	s_setprio 0
	s_barrier
	s_add_i32 s86, 0, 0x14000
	s_add_i32 s17, s17, s71
	v_add_u32_e32 v16, s86, v159
	ds_read_b128 v[198:201], v16
	ds_read_b128 v[230:233], v16 offset:1024
	ds_read_b128 v[234:237], v16 offset:2048
	ds_read_b128 v[238:241], v16 offset:3072
	v_lshl_add_u64 v[156:157], s[10:11], 0, v[136:137]
	s_mov_b32 m0, s17
	global_load_lds_dwordx4 v[156:157], off
	v_lshl_add_u64 v[242:243], s[10:11], 0, v[132:133]
	s_add_i32 m0, s17, 0x2000
	s_nop 0
	global_load_lds_dwordx4 v[242:243], off
	s_barrier
	s_waitcnt lgkmcnt(0)
	s_setprio 1
	s_waitcnt lgkmcnt(0)
	v_mfma_f32_16x16x32_f16 v[118:121], v[198:201], v[166:169], v[118:121]
	v_mfma_f32_16x16x32_f16 v[114:117], v[234:237], v[166:169], v[114:117]
	v_mfma_f32_16x16x32_f16 v[102:105], v[198:201], v[174:177], v[102:105]
	v_mfma_f32_16x16x32_f16 v[98:101], v[234:237], v[174:177], v[98:101]
	v_mfma_f32_16x16x32_f16 v[86:89], v[198:201], v[182:185], v[86:89]
	v_mfma_f32_16x16x32_f16 v[82:85], v[234:237], v[182:185], v[82:85]
	v_mfma_f32_16x16x32_f16 v[70:73], v[198:201], v[190:193], v[70:73]
	v_mfma_f32_16x16x32_f16 v[66:69], v[234:237], v[190:193], v[66:69]
	v_mfma_f32_16x16x32_f16 v[118:121], v[230:233], v[170:173], v[118:121]
	v_mfma_f32_16x16x32_f16 v[114:117], v[238:241], v[170:173], v[114:117]
	v_mfma_f32_16x16x32_f16 v[102:105], v[230:233], v[178:181], v[102:105]
	v_mfma_f32_16x16x32_f16 v[98:101], v[238:241], v[178:181], v[98:101]
	v_mfma_f32_16x16x32_f16 v[86:89], v[230:233], v[186:189], v[86:89]
	v_mfma_f32_16x16x32_f16 v[82:85], v[238:241], v[186:189], v[82:85]
	v_mfma_f32_16x16x32_f16 v[70:73], v[230:233], v[194:197], v[70:73]
	v_mfma_f32_16x16x32_f16 v[66:69], v[238:241], v[194:197], v[66:69]
	s_setprio 0
	s_barrier
	ds_read_b128 v[166:169], v161 offset:16384
	ds_read_b128 v[170:173], v161 offset:17408
	ds_read_b128 v[174:177], v161 offset:18432
	ds_read_b128 v[178:181], v161 offset:19456
	ds_read_b128 v[182:185], v161 offset:20480
	ds_read_b128 v[186:189], v161 offset:21504
	ds_read_b128 v[190:193], v161 offset:22528
	ds_read_b128 v[194:197], v161 offset:23552
	s_mov_b32 m0, s82
	v_lshl_add_u64 v[244:245], s[8:9], 0, v[134:135]
	global_load_lds_dwordx4 v[244:245], off
	v_lshl_add_u64 v[246:247], s[8:9], 0, v[130:131]
	s_mov_b32 m0, s83
	s_nop 0
	global_load_lds_dwordx4 v[246:247], off
	s_waitcnt vmcnt(10)
	s_barrier
	s_waitcnt lgkmcnt(0)
	s_setprio 1
	s_waitcnt lgkmcnt(0)
	v_mfma_f32_16x16x32_f16 v[62:65], v[144:147], v[166:169], v[62:65]
	v_mfma_f32_16x16x32_f16 v[58:61], v[152:155], v[166:169], v[58:61]
	v_mfma_f32_16x16x32_f16 v[46:49], v[144:147], v[174:177], v[46:49]
	v_mfma_f32_16x16x32_f16 v[42:45], v[152:155], v[174:177], v[42:45]
	v_mfma_f32_16x16x32_f16 v[30:33], v[144:147], v[182:185], v[30:33]
	v_mfma_f32_16x16x32_f16 v[26:29], v[152:155], v[182:185], v[26:29]
	v_mfma_f32_16x16x32_f16 v[12:15], v[144:147], v[190:193], v[12:15]
	v_mfma_f32_16x16x32_f16 v[8:11], v[152:155], v[190:193], v[8:11]
	v_mfma_f32_16x16x32_f16 v[62:65], v[148:151], v[170:173], v[62:65]
	v_mfma_f32_16x16x32_f16 v[58:61], v[162:165], v[170:173], v[58:61]
	v_mfma_f32_16x16x32_f16 v[46:49], v[148:151], v[178:181], v[46:49]
	v_mfma_f32_16x16x32_f16 v[42:45], v[162:165], v[178:181], v[42:45]
	v_mfma_f32_16x16x32_f16 v[30:33], v[148:151], v[186:189], v[30:33]
	v_mfma_f32_16x16x32_f16 v[26:29], v[162:165], v[186:189], v[26:29]
	v_mfma_f32_16x16x32_f16 v[12:15], v[148:151], v[194:197], v[12:15]
	v_mfma_f32_16x16x32_f16 v[8:11], v[162:165], v[194:197], v[8:11]
	s_setprio 0
	s_barrier
; #define PG8_STAGE(bufoff, gbase, voff) do { _Pragma("unroll") for (int _i = 0; _i < 2; ++_i) \
;         __builtin_amdgcn_global_load_lds((const unsigned*)((const char*)(gbase) + (voff)[_i]), (LAS unsigned*)(lds + (bufoff) + ldsw + _i * 8192), 16, 0, 0); } while (0)
; #define PG8_LDA(dst, b, h) do { _Pragma("unroll") for (int m = 0; m < 4; ++m) _Pragma("unroll") for (int k = 0; k < 2; ++k) dst[m][k] = *(const LAS f16x8*)(lds + PG8_SA(b, h) + aoff + m * 2048 + k * 1024); } while (0)
; #define PG8_LDB(dst, b, h) do { _Pragma("unroll") for (int n = 0; n < 2; ++n) _Pragma("unroll") for (int k = 0; k < 2; ++k) dst[n][k] = *(const LAS f16x8*)(lds + PG8_SB(b, h) + boff + n * 2048 + k * 1024); } while (0)
; #define PG8_MMA(ai, bj, At, Bt) do { __builtin_amdgcn_s_setprio(1); _Pragma("unroll") for (int m = 0; m < 4; ++m) _Pragma("unroll") for (int n = 0; n < 2; ++n) _Pragma("unroll") for (int k = 0; k < 2; ++k) \
;         acc[ai][bj][m][n] = __builtin_amdgcn_mfma_f32_16x16x32_f16(Bt[n][k], At[m][k], acc[ai][bj][m][n], 0, 0, 0); __builtin_amdgcn_s_setprio(0); } while (0)
; #define PG8_WAIT_V(n) asm volatile("s_waitcnt vmcnt(" #n ")" ::: "memory")
; #define PG8_WAIT_L(n) asm volatile("s_waitcnt lgkmcnt(" #n ")" ::: "memory")
; #define PG8_BAR __builtin_amdgcn_s_barrier()
; #define PG8_SCHED __builtin_amdgcn_sched_barrier(0)
; template <class Epi, class Sched>
; __device__ __forceinline__ void gemm_phase(LAS unsigned char* lds, const Gemm g, const Sched& S, const Epi& E) {
;     ...
;             PG8_STAGE(PG8_SB(0, 1), b2 + hstep, voffB);
;             PG8_WAIT_V(6); PG8_BAR; PG8_MMA(1, 1, At, B1); PG8_BAR;
;             PG8_LDB(B0, 1, 0); PG8_SCHED; PG8_LDA(At, 1, 0); PG8_STAGE(PG8_SA(0, 1), a2 + hstep, voffA);
;             PG8_WAIT_L(8); PG8_BAR; PG8_WAIT_L(0); PG8_MMA(0, 0, At, B0); PG8_BAR; PG8_SCHED;
;             PG8_LDB(B1, 1, 1); PG8_STAGE(PG8_SB(1, 0), b3, voffB);
;             PG8_BAR; PG8_WAIT_L(0); PG8_MMA(0, 1, At, B1); PG8_BAR;
	v_add_u32_e32 v16, 0x18000, v159
	ds_read_b128 v[144:147], v16
	ds_read_b128 v[148:151], v16 offset:1024
	ds_read_b128 v[152:155], v16 offset:2048
	ds_read_b128 v[162:165], v16 offset:3072
	s_add_u32 s10, s10, s44
	s_addc_u32 s11, s11, 0
	s_add_i32 s17, s86, s71
	v_lshl_add_u64 v[248:249], s[10:11], 0, v[136:137]
	s_mov_b32 m0, s17
	v_lshl_add_u64 v[250:251], s[10:11], 0, v[132:133]
	global_load_lds_dwordx4 v[248:249], off
	s_add_i32 m0, s17, 0x2000
	s_nop 0
	global_load_lds_dwordx4 v[250:251], off
	s_waitcnt vmcnt(6)
	s_barrier
	s_setprio 1
	v_mfma_f32_16x16x32_f16 v[54:57], v[198:201], v[166:169], v[54:57]
	v_mfma_f32_16x16x32_f16 v[50:53], v[234:237], v[166:169], v[50:53]
	v_mfma_f32_16x16x32_f16 v[38:41], v[198:201], v[174:177], v[38:41]
	v_mfma_f32_16x16x32_f16 v[34:37], v[234:237], v[174:177], v[34:37]
	v_mfma_f32_16x16x32_f16 v[22:25], v[198:201], v[182:185], v[22:25]
	v_mfma_f32_16x16x32_f16 v[18:21], v[234:237], v[182:185], v[18:21]
	v_mfma_f32_16x16x32_f16 v[4:7], v[198:201], v[190:193], v[4:7]
	v_mfma_f32_16x16x32_f16 v[0:3], v[234:237], v[190:193], v[0:3]
	v_mfma_f32_16x16x32_f16 v[54:57], v[230:233], v[170:173], v[54:57]
	v_mfma_f32_16x16x32_f16 v[50:53], v[238:241], v[170:173], v[50:53]
	v_mfma_f32_16x16x32_f16 v[38:41], v[230:233], v[178:181], v[38:41]
	v_mfma_f32_16x16x32_f16 v[34:37], v[238:241], v[178:181], v[34:37]
	v_mfma_f32_16x16x32_f16 v[22:25], v[230:233], v[186:189], v[22:25]
	v_mfma_f32_16x16x32_f16 v[18:21], v[238:241], v[186:189], v[18:21]
	v_mfma_f32_16x16x32_f16 v[4:7], v[230:233], v[194:197], v[4:7]
	v_mfma_f32_16x16x32_f16 v[0:3], v[238:241], v[194:197], v[0:3]
	s_setprio 0
	s_barrier
	ds_read_b128 v[166:169], v161 offset:32768
	ds_read_b128 v[170:173], v161 offset:33792
	ds_read_b128 v[174:177], v161 offset:34816
	ds_read_b128 v[178:181], v161 offset:35840
	ds_read_b128 v[182:185], v161 offset:36864
	ds_read_b128 v[186:189], v161 offset:37888
	ds_read_b128 v[190:193], v161 offset:38912
	ds_read_b128 v[194:197], v161 offset:39936
	s_add_i32 s10, 0, 0x18000
	s_add_u32 s8, s8, s44
	s_addc_u32 s9, s9, 0
	s_mov_b32 m0, s84
	v_lshl_add_u64 v[198:199], s[8:9], 0, v[134:135]
	global_load_lds_dwordx4 v[198:199], off
	v_lshl_add_u64 v[198:199], s[8:9], 0, v[130:131]
	s_mov_b32 m0, s85
	s_nop 0
	global_load_lds_dwordx4 v[198:199], off
	s_waitcnt lgkmcnt(8)
	s_barrier
	s_waitcnt lgkmcnt(0)
	s_setprio 1
	s_waitcnt lgkmcnt(0)
	v_mfma_f32_16x16x32_f16 v[126:129], v[144:147], v[166:169], v[126:129]
	v_mfma_f32_16x16x32_f16 v[122:125], v[152:155], v[166:169], v[122:125]
	v_mfma_f32_16x16x32_f16 v[110:113], v[144:147], v[174:177], v[110:113]
	v_mfma_f32_16x16x32_f16 v[106:109], v[152:155], v[174:177], v[106:109]
	v_mfma_f32_16x16x32_f16 v[94:97], v[144:147], v[182:185], v[94:97]
	v_mfma_f32_16x16x32_f16 v[90:93], v[152:155], v[182:185], v[90:93]
	v_mfma_f32_16x16x32_f16 v[78:81], v[144:147], v[190:193], v[78:81]
	v_mfma_f32_16x16x32_f16 v[74:77], v[152:155], v[190:193], v[74:77]
	v_mfma_f32_16x16x32_f16 v[126:129], v[148:151], v[170:173], v[126:129]
	v_mfma_f32_16x16x32_f16 v[122:125], v[162:165], v[170:173], v[122:125]
	v_mfma_f32_16x16x32_f16 v[110:113], v[148:151], v[178:181], v[110:113]
	v_mfma_f32_16x16x32_f16 v[106:109], v[162:165], v[178:181], v[106:109]
	v_mfma_f32_16x16x32_f16 v[94:97], v[148:151], v[186:189], v[94:97]
	v_mfma_f32_16x16x32_f16 v[90:93], v[162:165], v[186:189], v[90:93]
	v_mfma_f32_16x16x32_f16 v[78:81], v[148:151], v[194:197], v[78:81]
	v_mfma_f32_16x16x32_f16 v[74:77], v[162:165], v[194:197], v[74:77]
	s_setprio 0
	s_barrier
	s_add_i32 s8, 0, 0x1c000
	s_add_i32 s9, s10, s71
	v_add_u32_e32 v16, s8, v159
	ds_read_b128 v[198:201], v16
	ds_read_b128 v[230:233], v16 offset:1024
	ds_read_b128 v[234:237], v16 offset:2048
	ds_read_b128 v[238:241], v16 offset:3072
	v_lshl_add_u64 v[156:157], v[156:157], 0, s[90:91]
	s_mov_b32 m0, s9
	global_load_lds_dwordx4 v[156:157], off
	v_lshl_add_u64 v[156:157], v[242:243], 0, s[90:91]
	s_add_i32 m0, s9, 0x2000
	s_nop 0
	global_load_lds_dwordx4 v[156:157], off
	s_barrier
	s_waitcnt lgkmcnt(0)
	s_setprio 1
	s_waitcnt lgkmcnt(0)
	v_mfma_f32_16x16x32_f16 v[118:121], v[198:201], v[166:169], v[118:121]
	v_mfma_f32_16x16x32_f16 v[114:117], v[234:237], v[166:169], v[114:117]
	v_mfma_f32_16x16x32_f16 v[102:105], v[198:201], v[174:177], v[102:105]
	v_mfma_f32_16x16x32_f16 v[98:101], v[234:237], v[174:177], v[98:101]
	v_mfma_f32_16x16x32_f16 v[86:89], v[198:201], v[182:185], v[86:89]
	v_mfma_f32_16x16x32_f16 v[82:85], v[234:237], v[182:185], v[82:85]
	v_mfma_f32_16x16x32_f16 v[70:73], v[198:201], v[190:193], v[70:73]
	v_mfma_f32_16x16x32_f16 v[66:69], v[234:237], v[190:193], v[66:69]
	v_mfma_f32_16x16x32_f16 v[118:121], v[230:233], v[170:173], v[118:121]
	v_mfma_f32_16x16x32_f16 v[114:117], v[238:241], v[170:173], v[114:117]
	v_mfma_f32_16x16x32_f16 v[102:105], v[230:233], v[178:181], v[102:105]
	v_mfma_f32_16x16x32_f16 v[98:101], v[238:241], v[178:181], v[98:101]
	v_mfma_f32_16x16x32_f16 v[86:89], v[230:233], v[186:189], v[86:89]
	v_mfma_f32_16x16x32_f16 v[82:85], v[238:241], v[186:189], v[82:85]
	v_mfma_f32_16x16x32_f16 v[70:73], v[230:233], v[194:197], v[70:73]
	v_mfma_f32_16x16x32_f16 v[66:69], v[238:241], v[194:197], v[66:69]
	s_setprio 0
	s_barrier
; #define PG8_STAGE(bufoff, gbase, voff) do { _Pragma("unroll") for (int _i = 0; _i < 2; ++_i) \
;         __builtin_amdgcn_global_load_lds((const unsigned*)((const char*)(gbase) + (voff)[_i]), (LAS unsigned*)(lds + (bufoff) + ldsw + _i * 8192), 16, 0, 0); } while (0)
; #define PG8_LDA(dst, b, h) do { _Pragma("unroll") for (int m = 0; m < 4; ++m) _Pragma("unroll") for (int k = 0; k < 2; ++k) dst[m][k] = *(const LAS f16x8*)(lds + PG8_SA(b, h) + aoff + m * 2048 + k * 1024); } while (0)
; #define PG8_MMA(ai, bj, At, Bt) do { __builtin_amdgcn_s_setprio(1); _Pragma("unroll") for (int m = 0; m < 4; ++m) _Pragma("unroll") for (int n = 0; n < 2; ++n) _Pragma("unroll") for (int k = 0; k < 2; ++k) \
;         acc[ai][bj][m][n] = __builtin_amdgcn_mfma_f32_16x16x32_f16(Bt[n][k], At[m][k], acc[ai][bj][m][n], 0, 0, 0); __builtin_amdgcn_s_setprio(0); } while (0)
;     __device__ __forceinline__ void operator()(const f32x4 (&acc)[2][2][4][2], const Unit& u, int wr, int wc, int fr, int fq) const {
;     ...
;             f16_t* O = (f16_t*)out;
;             const int row0 = u.pm * BM + wr * 64 + fr; const int col0 = u.pn * BM + wc * 32 + 8 * fq;
;             const float lo = mode == 1 ? 0.f : -3.0e38f;
; #pragma unroll
;             for (int ai = 0; ai < 2; ++ai)
; #pragma unroll
;                 for (int m = 0; m < 4; ++m) { f16_t* rowp = O + (size_t)(row0 + ai * HALF + m * 16) * ldc + col0;
; #pragma unroll
;                     for (int bj = 0; bj < 2; ++bj) { f32x4 v0 = acc[ai][bj][m][0], v1 = acc[ai][bj][m][1];
;                         if (mode == 1) {
; #pragma unroll
;                             for (int j = 0; j < 4; ++j) { float a = fmaxf(v0[j], lo), b = fmaxf(v1[j], lo); v0[j] = a * a; v1[j] = b * b; } }
;                         u32x4 w; w.x = pkh(v0[0], v0[1]); w.y = pkh(v0[2], v0[3]); w.z = pkh(v1[0], v1[1]); w.w = pkh(v1[2], v1[3]);
;                         *(u32x4*)(rowp + bj * HALF) = w; } }
; template <class Epi, class Sched>
; __device__ __forceinline__ void gemm_phase(LAS unsigned char* lds, const Gemm g, const Sched& S, const Epi& E) {
;     ...
;             PG8_LDA(At, 1, 1); PG8_STAGE(PG8_SA(1, 0), a3, voffA);
;             PG8_BAR; PG8_WAIT_L(0); PG8_MMA(1, 0, At, B0); PG8_BAR; PG8_SCHED;
;             PG8_STAGE(PG8_SB(1, 1), b3 + hstep, voffB);
;             PG8_WAIT_V(6); PG8_BAR; PG8_MMA(1, 1, At, B1); PG8_BAR;
;         }
	ds_read_b128 v[166:169], v161 offset:49152
	ds_read_b128 v[170:173], v161 offset:50176
	ds_read_b128 v[174:177], v161 offset:51200
	ds_read_b128 v[178:181], v161 offset:52224
	ds_read_b128 v[182:185], v161 offset:53248
	ds_read_b128 v[186:189], v161 offset:54272
	ds_read_b128 v[190:193], v161 offset:55296
	ds_read_b128 v[194:197], v161 offset:56320
	s_mov_b32 m0, s94
	v_lshl_add_u64 v[156:157], v[244:245], 0, s[90:91]
	global_load_lds_dwordx4 v[156:157], off
	v_lshl_add_u64 v[156:157], v[246:247], 0, s[90:91]
	s_mov_b32 m0, s95
	s_nop 0
	global_load_lds_dwordx4 v[156:157], off
	s_waitcnt vmcnt(10)
	s_barrier
	s_waitcnt lgkmcnt(0)
	s_setprio 1
	s_waitcnt lgkmcnt(0)
	v_mfma_f32_16x16x32_f16 v[62:65], v[144:147], v[166:169], v[62:65]
	v_mfma_f32_16x16x32_f16 v[58:61], v[152:155], v[166:169], v[58:61]
	v_mfma_f32_16x16x32_f16 v[46:49], v[144:147], v[174:177], v[46:49]
	v_mfma_f32_16x16x32_f16 v[42:45], v[152:155], v[174:177], v[42:45]
	v_mfma_f32_16x16x32_f16 v[30:33], v[144:147], v[182:185], v[30:33]
	v_mfma_f32_16x16x32_f16 v[26:29], v[152:155], v[182:185], v[26:29]
	v_mfma_f32_16x16x32_f16 v[12:15], v[144:147], v[190:193], v[12:15]
	v_mfma_f32_16x16x32_f16 v[8:11], v[152:155], v[190:193], v[8:11]
	v_mfma_f32_16x16x32_f16 v[62:65], v[148:151], v[170:173], v[62:65]
	v_mfma_f32_16x16x32_f16 v[58:61], v[162:165], v[170:173], v[58:61]
	v_mfma_f32_16x16x32_f16 v[46:49], v[148:151], v[178:181], v[46:49]
	v_mfma_f32_16x16x32_f16 v[42:45], v[162:165], v[178:181], v[42:45]
	v_mfma_f32_16x16x32_f16 v[30:33], v[148:151], v[186:189], v[30:33]
	v_mfma_f32_16x16x32_f16 v[26:29], v[162:165], v[186:189], v[26:29]
	v_mfma_f32_16x16x32_f16 v[12:15], v[148:151], v[194:197], v[12:15]
	v_mfma_f32_16x16x32_f16 v[8:11], v[162:165], v[194:197], v[8:11]
	s_setprio 0
	s_barrier
	v_add_u32_e32 v16, 0x10000, v159
	ds_read_b128 v[144:147], v16
	ds_read_b128 v[148:151], v16 offset:1024
	ds_read_b128 v[152:155], v16 offset:2048
	ds_read_b128 v[162:165], v16 offset:3072
	s_add_u32 s6, s6, 0x100
	s_addc_u32 s7, s7, 0
	s_add_u32 s41, s41, 0x100
	s_addc_u32 vcc_lo, vcc_lo, 0
	s_add_i32 s8, s8, s71
	v_lshl_add_u64 v[156:157], v[248:249], 0, s[90:91]
	s_mov_b32 m0, s8
	s_nop 0
	global_load_lds_dwordx4 v[156:157], off
	v_lshl_add_u64 v[156:157], v[250:251], 0, s[90:91]
	s_add_i32 m0, s8, 0x2000
	s_nop 0
	global_load_lds_dwordx4 v[156:157], off
	s_waitcnt vmcnt(6)
	s_barrier
	s_setprio 1
	v_mfma_f32_16x16x32_f16 v[54:57], v[198:201], v[166:169], v[54:57]
	v_mfma_f32_16x16x32_f16 v[50:53], v[234:237], v[166:169], v[50:53]
	v_mfma_f32_16x16x32_f16 v[38:41], v[198:201], v[174:177], v[38:41]
	v_mfma_f32_16x16x32_f16 v[34:37], v[234:237], v[174:177], v[34:37]
	v_mfma_f32_16x16x32_f16 v[22:25], v[198:201], v[182:185], v[22:25]
	v_mfma_f32_16x16x32_f16 v[18:21], v[234:237], v[182:185], v[18:21]
	v_mfma_f32_16x16x32_f16 v[4:7], v[198:201], v[190:193], v[4:7]
	v_mfma_f32_16x16x32_f16 v[0:3], v[234:237], v[190:193], v[0:3]
	v_mfma_f32_16x16x32_f16 v[54:57], v[230:233], v[170:173], v[54:57]
	v_mfma_f32_16x16x32_f16 v[50:53], v[238:241], v[170:173], v[50:53]
	v_mfma_f32_16x16x32_f16 v[38:41], v[230:233], v[178:181], v[38:41]
	v_mfma_f32_16x16x32_f16 v[34:37], v[238:241], v[178:181], v[34:37]
	v_mfma_f32_16x16x32_f16 v[22:25], v[230:233], v[186:189], v[22:25]
	v_mfma_f32_16x16x32_f16 v[18:21], v[238:241], v[186:189], v[18:21]
	v_mfma_f32_16x16x32_f16 v[4:7], v[230:233], v[194:197], v[4:7]
	v_mfma_f32_16x16x32_f16 v[0:3], v[238:241], v[194:197], v[0:3]
	s_setprio 0
	s_barrier
	s_cmp_ge_u32 vcc_hi, s77
	s_mov_b32 s8, vcc_hi
	s_cbranch_scc0 .LBB0_829
	s_waitcnt lgkmcnt(0)
	v_lshl_add_u32 v162, s36, 8, v139
	v_ashrrev_i32_e32 v16, 31, v162
	s_lshl_b32 s3, s3, 8
	v_mul_lo_u32 v163, s54, v16
	v_mul_lo_u32 v16, s55, v162
	v_mad_u64_u32 v[144:145], s[6:7], s54, v162, 0
	s_or_b32 s3, s3, s89
	v_add3_u32 v145, v145, v163, v16
	s_mov_b64 s[6:7], -1
	s_and_b64 vcc, exec, s[42:43]
	s_movk_i32 s86, 0x41ff
	s_cbranch_vccz .LBB0_864
	v_cndmask_b32_e64 v16, 0, 1, s[48:49]
	v_cmp_ne_u32_e64 s[40:41], 1, v16
	s_andn2_b64 vcc, exec, s[48:49]
	v_or_b32_e32 v16, s3, v158
	v_lshlrev_b32_e32 v16, 1, v16
	v_lshl_add_u64 v[146:147], s[52:53], 0, v[16:17]
	v_lshl_add_u64 v[148:149], v[144:145], 1, v[146:147]
	s_cbranch_vccnz .Lep0_0
	v_max_f32_e32 v150, 0, v126
	v_max_f32_e32 v151, 0, v127
	v_max_f32_e32 v152, 0, v128
	v_max_f32_e32 v153, 0, v129
	v_max_f32_e32 v154, 0, v122
	v_max_f32_e32 v155, 0, v123
	v_max_f32_e32 v156, 0, v124
	v_max_f32_e32 v157, 0, v125
	v_pk_mul_f32 v[150:151], v[150:151], v[150:151]
	v_pk_mul_f32 v[152:153], v[152:153], v[152:153]
	v_pk_mul_f32 v[154:155], v[154:155], v[154:155]
	v_pk_mul_f32 v[156:157], v[156:157], v[156:157]
	v_cvt_pk_f16_f32 v150, v150, v151
	v_cvt_pk_f16_f32 v151, v152, v153
	v_cvt_pk_f16_f32 v152, v154, v155
	v_cvt_pk_f16_f32 v153, v156, v157
	s_branch .Lep1_0
